# SwiGLU epilogue: packed f32 multiply/add for the sigmoid argument and +1, same operation order
# baseline (speedup 1.0000x reference)
.LBB0_191:
	s_add_u32 s36, s44, 0xfffc0080
	s_addc_u32 s37, s45, -1
	s_add_i32 s38, 0, 0x10000
	v_add_u32_e32 v152, s38, v142
	ds_read_b128 v[138:141], v152
	ds_read_b128 v[144:147], v152 offset:1024
	ds_read_b128 v[148:151], v152 offset:2048
	ds_read_b128 v[152:155], v152 offset:3072
	s_cmp_eq_u32 s61, 12
	s_cselect_b32 s49, s13, s37
	s_cselect_b32 s48, s34, s36
	s_cselect_b32 s47, s9, s60
	s_cselect_b32 s46, s35, s59
	v_lshl_add_u64 v[172:173], s[44:45], 0, v[134:135]
	s_add_i32 m0, s30, 0xc000
	ds_read_b128 v[156:159], v143
	ds_read_b128 v[160:163], v143 offset:1024
	ds_read_b128 v[164:167], v143 offset:2048
	ds_read_b128 v[180:183], v143 offset:3072
	ds_read_b128 v[184:187], v143 offset:4096
	ds_read_b128 v[188:191], v143 offset:5120
	ds_read_b128 v[192:195], v143 offset:6144
	ds_read_b128 v[196:199], v143 offset:7168
	global_load_lds_dwordx4 v[172:173], off
	v_lshl_add_u64 v[172:173], s[44:45], 0, v[136:137]
	s_add_i32 m0, s30, 0xe000
	s_nop 0
	global_load_lds_dwordx4 v[172:173], off
	s_waitcnt lgkmcnt(8)
	s_barrier
	s_waitcnt lgkmcnt(0)
	s_setprio 1
	s_waitcnt lgkmcnt(0)
	v_mfma_f32_16x16x32_bf16 v[124:127], v[138:141], v[156:159], v[124:127]
	v_mfma_f32_16x16x32_bf16 v[116:119], v[148:151], v[156:159], v[116:119]
	v_mfma_f32_16x16x32_bf16 v[108:111], v[138:141], v[164:167], v[108:111]
	v_mfma_f32_16x16x32_bf16 v[100:103], v[148:151], v[164:167], v[100:103]
	v_mfma_f32_16x16x32_bf16 v[92:95], v[138:141], v[184:187], v[92:95]
	v_mfma_f32_16x16x32_bf16 v[84:87], v[148:151], v[184:187], v[84:87]
	v_mfma_f32_16x16x32_bf16 v[76:79], v[138:141], v[192:195], v[76:79]
	v_mfma_f32_16x16x32_bf16 v[68:71], v[148:151], v[192:195], v[68:71]
	v_mfma_f32_16x16x32_bf16 v[124:127], v[144:147], v[160:163], v[124:127]
	v_mfma_f32_16x16x32_bf16 v[116:119], v[152:155], v[160:163], v[116:119]
	v_mfma_f32_16x16x32_bf16 v[108:111], v[144:147], v[180:183], v[108:111]
	v_mfma_f32_16x16x32_bf16 v[100:103], v[152:155], v[180:183], v[100:103]
	v_mfma_f32_16x16x32_bf16 v[92:95], v[144:147], v[188:191], v[92:95]
	v_mfma_f32_16x16x32_bf16 v[84:87], v[152:155], v[188:191], v[84:87]
	v_mfma_f32_16x16x32_bf16 v[76:79], v[144:147], v[196:199], v[76:79]
	v_mfma_f32_16x16x32_bf16 v[68:71], v[152:155], v[196:199], v[68:71]
	s_setprio 0
	s_barrier
	s_add_i32 s39, 0, 0x14000
	v_add_u32_e32 v172, s39, v142
	s_add_i32 s36, s38, s29
	ds_read_b128 v[200:203], v172
	ds_read_b128 v[204:207], v172 offset:1024
	ds_read_b128 v[208:211], v172 offset:2048
	ds_read_b128 v[212:215], v172 offset:3072
	v_lshl_add_u64 v[172:173], s[46:47], 0, v[168:169]
	s_mov_b32 m0, s36
	v_lshl_add_u64 v[174:175], s[46:47], 0, v[128:129]
	global_load_lds_dwordx4 v[172:173], off
	s_add_i32 m0, s36, 0x2000
	s_nop 0
	global_load_lds_dwordx4 v[174:175], off
	s_barrier
	s_waitcnt lgkmcnt(0)
	s_setprio 1
	s_waitcnt lgkmcnt(0)
	v_mfma_f32_16x16x32_bf16 v[120:123], v[200:203], v[156:159], v[120:123]
	v_mfma_f32_16x16x32_bf16 v[112:115], v[208:211], v[156:159], v[112:115]
	v_mfma_f32_16x16x32_bf16 v[104:107], v[200:203], v[164:167], v[104:107]
	v_mfma_f32_16x16x32_bf16 v[96:99], v[208:211], v[164:167], v[96:99]
	v_mfma_f32_16x16x32_bf16 v[88:91], v[200:203], v[184:187], v[88:91]
	v_mfma_f32_16x16x32_bf16 v[80:83], v[208:211], v[184:187], v[80:83]
	v_mfma_f32_16x16x32_bf16 v[72:75], v[200:203], v[192:195], v[72:75]
	v_mfma_f32_16x16x32_bf16 v[64:67], v[208:211], v[192:195], v[64:67]
	v_mfma_f32_16x16x32_bf16 v[120:123], v[204:207], v[160:163], v[120:123]
	v_mfma_f32_16x16x32_bf16 v[112:115], v[212:215], v[160:163], v[112:115]
	v_mfma_f32_16x16x32_bf16 v[104:107], v[204:207], v[180:183], v[104:107]
	v_mfma_f32_16x16x32_bf16 v[96:99], v[212:215], v[180:183], v[96:99]
	v_mfma_f32_16x16x32_bf16 v[88:91], v[204:207], v[188:191], v[88:91]
	v_mfma_f32_16x16x32_bf16 v[80:83], v[212:215], v[188:191], v[80:83]
	v_mfma_f32_16x16x32_bf16 v[72:75], v[204:207], v[196:199], v[72:75]
	v_mfma_f32_16x16x32_bf16 v[64:67], v[212:215], v[196:199], v[64:67]
	s_setprio 0
	s_mov_b32 m0, s30
	v_lshl_add_u64 v[176:177], s[48:49], 0, v[132:133]
	s_barrier
	ds_read_b128 v[156:159], v143 offset:16384
	ds_read_b128 v[160:163], v143 offset:17408
	ds_read_b128 v[164:167], v143 offset:18432
	ds_read_b128 v[180:183], v143 offset:19456
	ds_read_b128 v[184:187], v143 offset:20480
	ds_read_b128 v[188:191], v143 offset:21504
	ds_read_b128 v[192:195], v143 offset:22528
	ds_read_b128 v[196:199], v143 offset:23552
	global_load_lds_dwordx4 v[176:177], off
	v_lshl_add_u64 v[178:179], s[48:49], 0, v[130:131]
	s_mov_b32 m0, s31
	s_nop 0
	global_load_lds_dwordx4 v[178:179], off
	s_barrier
	s_waitcnt lgkmcnt(0)
	s_setprio 1
	s_waitcnt lgkmcnt(0)
	v_mfma_f32_16x16x32_bf16 v[60:63], v[138:141], v[156:159], v[60:63]
	v_mfma_f32_16x16x32_bf16 v[52:55], v[148:151], v[156:159], v[52:55]
	v_mfma_f32_16x16x32_bf16 v[44:47], v[138:141], v[164:167], v[44:47]
	v_mfma_f32_16x16x32_bf16 v[36:39], v[148:151], v[164:167], v[36:39]
	v_mfma_f32_16x16x32_bf16 v[28:31], v[138:141], v[184:187], v[28:31]
	v_mfma_f32_16x16x32_bf16 v[20:23], v[148:151], v[184:187], v[20:23]
	v_mfma_f32_16x16x32_bf16 v[12:15], v[138:141], v[192:195], v[12:15]
	v_mfma_f32_16x16x32_bf16 v[4:7], v[148:151], v[192:195], v[4:7]
	v_mfma_f32_16x16x32_bf16 v[60:63], v[144:147], v[160:163], v[60:63]
	v_mfma_f32_16x16x32_bf16 v[52:55], v[152:155], v[160:163], v[52:55]
	v_mfma_f32_16x16x32_bf16 v[44:47], v[144:147], v[180:183], v[44:47]
	v_mfma_f32_16x16x32_bf16 v[36:39], v[152:155], v[180:183], v[36:39]
	v_mfma_f32_16x16x32_bf16 v[28:31], v[144:147], v[188:191], v[28:31]
	v_mfma_f32_16x16x32_bf16 v[20:23], v[152:155], v[188:191], v[20:23]
	v_mfma_f32_16x16x32_bf16 v[12:15], v[144:147], v[196:199], v[12:15]
	v_mfma_f32_16x16x32_bf16 v[4:7], v[152:155], v[196:199], v[4:7]
	s_setprio 0
	s_barrier
	s_add_u32 s36, s46, 0x40000
	s_addc_u32 s37, s47, 0
	s_add_i32 s38, s39, s29
	v_lshl_add_u64 v[138:139], s[36:37], 0, v[168:169]
	s_mov_b32 m0, s38
	s_nop 0
	global_load_lds_dwordx4 v[138:139], off
	v_lshl_add_u64 v[138:139], s[36:37], 0, v[128:129]
	s_add_i32 m0, s38, 0x2000
	s_nop 0
	global_load_lds_dwordx4 v[138:139], off
	s_waitcnt vmcnt(6)
	s_barrier
	s_setprio 1
	v_mfma_f32_16x16x32_bf16 v[56:59], v[200:203], v[156:159], v[56:59]
	v_mfma_f32_16x16x32_bf16 v[48:51], v[208:211], v[156:159], v[48:51]
	v_mfma_f32_16x16x32_bf16 v[40:43], v[200:203], v[164:167], v[40:43]
	v_mfma_f32_16x16x32_bf16 v[32:35], v[208:211], v[164:167], v[32:35]
	v_mfma_f32_16x16x32_bf16 v[24:27], v[200:203], v[184:187], v[24:27]
	v_mfma_f32_16x16x32_bf16 v[16:19], v[208:211], v[184:187], v[16:19]
	v_mfma_f32_16x16x32_bf16 v[8:11], v[200:203], v[192:195], v[8:11]
	v_mfma_f32_16x16x32_bf16 v[0:3], v[208:211], v[192:195], v[0:3]
	v_mfma_f32_16x16x32_bf16 v[56:59], v[204:207], v[160:163], v[56:59]
	v_mfma_f32_16x16x32_bf16 v[48:51], v[212:215], v[160:163], v[48:51]
	v_mfma_f32_16x16x32_bf16 v[40:43], v[204:207], v[180:183], v[40:43]
	v_mfma_f32_16x16x32_bf16 v[32:35], v[212:215], v[180:183], v[32:35]
	v_mfma_f32_16x16x32_bf16 v[24:27], v[204:207], v[188:191], v[24:27]
	v_mfma_f32_16x16x32_bf16 v[16:19], v[212:215], v[188:191], v[16:19]
	v_mfma_f32_16x16x32_bf16 v[8:11], v[204:207], v[196:199], v[8:11]
	v_mfma_f32_16x16x32_bf16 v[0:3], v[212:215], v[196:199], v[0:3]
	s_setprio 0
	s_add_i32 s38, 0, 0x18000
	v_add_u32_e32 v152, s38, v142
	s_barrier
	ds_read_b128 v[138:141], v152
	ds_read_b128 v[144:147], v152 offset:1024
	ds_read_b128 v[148:151], v152 offset:2048
	ds_read_b128 v[152:155], v152 offset:3072
	s_add_u32 s36, s48, 0x40000
	s_addc_u32 s37, s49, 0
	s_mov_b32 m0, s50
	v_lshl_add_u64 v[200:201], s[36:37], 0, v[132:133]
	ds_read_b128 v[156:159], v143 offset:32768
	ds_read_b128 v[160:163], v143 offset:33792
	ds_read_b128 v[164:167], v143 offset:34816
	ds_read_b128 v[180:183], v143 offset:35840
	ds_read_b128 v[184:187], v143 offset:36864
	ds_read_b128 v[188:191], v143 offset:37888
	ds_read_b128 v[192:195], v143 offset:38912
	ds_read_b128 v[196:199], v143 offset:39936
	global_load_lds_dwordx4 v[200:201], off
	v_lshl_add_u64 v[200:201], s[36:37], 0, v[130:131]
	s_mov_b32 m0, s51
	s_nop 0
	global_load_lds_dwordx4 v[200:201], off
	s_waitcnt lgkmcnt(8)
	s_barrier
	s_waitcnt lgkmcnt(0)
	s_setprio 1
	s_waitcnt lgkmcnt(0)
	v_mfma_f32_16x16x32_bf16 v[124:127], v[138:141], v[156:159], v[124:127]
	v_mfma_f32_16x16x32_bf16 v[116:119], v[148:151], v[156:159], v[116:119]
	v_mfma_f32_16x16x32_bf16 v[108:111], v[138:141], v[164:167], v[108:111]
	v_mfma_f32_16x16x32_bf16 v[100:103], v[148:151], v[164:167], v[100:103]
	v_mfma_f32_16x16x32_bf16 v[92:95], v[138:141], v[184:187], v[92:95]
	v_mfma_f32_16x16x32_bf16 v[84:87], v[148:151], v[184:187], v[84:87]
	v_mfma_f32_16x16x32_bf16 v[76:79], v[138:141], v[192:195], v[76:79]
	v_mfma_f32_16x16x32_bf16 v[68:71], v[148:151], v[192:195], v[68:71]
	v_mfma_f32_16x16x32_bf16 v[124:127], v[144:147], v[160:163], v[124:127]
	v_mfma_f32_16x16x32_bf16 v[116:119], v[152:155], v[160:163], v[116:119]
	v_mfma_f32_16x16x32_bf16 v[108:111], v[144:147], v[180:183], v[108:111]
	v_mfma_f32_16x16x32_bf16 v[100:103], v[152:155], v[180:183], v[100:103]
	v_mfma_f32_16x16x32_bf16 v[92:95], v[144:147], v[188:191], v[92:95]
	v_mfma_f32_16x16x32_bf16 v[84:87], v[152:155], v[188:191], v[84:87]
	v_mfma_f32_16x16x32_bf16 v[76:79], v[144:147], v[196:199], v[76:79]
	v_mfma_f32_16x16x32_bf16 v[68:71], v[152:155], v[196:199], v[68:71]
	s_setprio 0
	s_barrier
	s_add_i32 s39, 0, 0x1c000
	s_add_i32 s36, s38, s29
	v_add_u32_e32 v212, s39, v142
	v_lshl_add_u64 v[172:173], v[172:173], 0, s[88:89]
	s_mov_b32 m0, s36
	ds_read_b128 v[200:203], v212
	ds_read_b128 v[204:207], v212 offset:1024
	ds_read_b128 v[208:211], v212 offset:2048
	ds_read_b128 v[212:215], v212 offset:3072
	global_load_lds_dwordx4 v[172:173], off
	v_lshl_add_u64 v[172:173], v[174:175], 0, s[88:89]
	s_add_i32 m0, s36, 0x2000
	s_nop 0
	global_load_lds_dwordx4 v[172:173], off
	s_barrier
	s_waitcnt lgkmcnt(0)
	s_setprio 1
	s_waitcnt lgkmcnt(0)
	v_mfma_f32_16x16x32_bf16 v[120:123], v[200:203], v[156:159], v[120:123]
	v_mfma_f32_16x16x32_bf16 v[112:115], v[208:211], v[156:159], v[112:115]
	v_mfma_f32_16x16x32_bf16 v[104:107], v[200:203], v[164:167], v[104:107]
	v_mfma_f32_16x16x32_bf16 v[96:99], v[208:211], v[164:167], v[96:99]
	v_mfma_f32_16x16x32_bf16 v[88:91], v[200:203], v[184:187], v[88:91]
	v_mfma_f32_16x16x32_bf16 v[80:83], v[208:211], v[184:187], v[80:83]
	v_mfma_f32_16x16x32_bf16 v[72:75], v[200:203], v[192:195], v[72:75]
	v_mfma_f32_16x16x32_bf16 v[64:67], v[208:211], v[192:195], v[64:67]
	v_mfma_f32_16x16x32_bf16 v[120:123], v[204:207], v[160:163], v[120:123]
	v_mfma_f32_16x16x32_bf16 v[112:115], v[212:215], v[160:163], v[112:115]
	v_mfma_f32_16x16x32_bf16 v[104:107], v[204:207], v[180:183], v[104:107]
	v_mfma_f32_16x16x32_bf16 v[96:99], v[212:215], v[180:183], v[96:99]
	v_mfma_f32_16x16x32_bf16 v[88:91], v[204:207], v[188:191], v[88:91]
	v_mfma_f32_16x16x32_bf16 v[80:83], v[212:215], v[188:191], v[80:83]
	v_mfma_f32_16x16x32_bf16 v[72:75], v[204:207], v[196:199], v[72:75]
	v_mfma_f32_16x16x32_bf16 v[64:67], v[212:215], v[196:199], v[64:67]
	s_setprio 0
	s_mov_b32 m0, s54
	v_lshl_add_u64 v[172:173], v[176:177], 0, s[88:89]
	s_barrier
	ds_read_b128 v[156:159], v143 offset:49152
	ds_read_b128 v[160:163], v143 offset:50176
	ds_read_b128 v[164:167], v143 offset:51200
	ds_read_b128 v[180:183], v143 offset:52224
	ds_read_b128 v[184:187], v143 offset:53248
	ds_read_b128 v[188:191], v143 offset:54272
	ds_read_b128 v[192:195], v143 offset:55296
	ds_read_b128 v[196:199], v143 offset:56320
	global_load_lds_dwordx4 v[172:173], off
	v_lshl_add_u64 v[172:173], v[178:179], 0, s[88:89]
	s_mov_b32 m0, s55
	s_nop 0
	global_load_lds_dwordx4 v[172:173], off
	s_barrier
	s_waitcnt lgkmcnt(0)
	s_setprio 1
	s_waitcnt lgkmcnt(0)
	v_mfma_f32_16x16x32_bf16 v[60:63], v[138:141], v[156:159], v[60:63]
	v_mfma_f32_16x16x32_bf16 v[52:55], v[148:151], v[156:159], v[52:55]
	v_mfma_f32_16x16x32_bf16 v[44:47], v[138:141], v[164:167], v[44:47]
	v_mfma_f32_16x16x32_bf16 v[36:39], v[148:151], v[164:167], v[36:39]
	v_mfma_f32_16x16x32_bf16 v[28:31], v[138:141], v[184:187], v[28:31]
	v_mfma_f32_16x16x32_bf16 v[20:23], v[148:151], v[184:187], v[20:23]
	v_mfma_f32_16x16x32_bf16 v[12:15], v[138:141], v[192:195], v[12:15]
	v_mfma_f32_16x16x32_bf16 v[4:7], v[148:151], v[192:195], v[4:7]
	v_mfma_f32_16x16x32_bf16 v[60:63], v[144:147], v[160:163], v[60:63]
	v_mfma_f32_16x16x32_bf16 v[52:55], v[152:155], v[160:163], v[52:55]
	v_mfma_f32_16x16x32_bf16 v[44:47], v[144:147], v[180:183], v[44:47]
	v_mfma_f32_16x16x32_bf16 v[36:39], v[152:155], v[180:183], v[36:39]
	v_mfma_f32_16x16x32_bf16 v[28:31], v[144:147], v[188:191], v[28:31]
	v_mfma_f32_16x16x32_bf16 v[20:23], v[152:155], v[188:191], v[20:23]
	v_mfma_f32_16x16x32_bf16 v[12:15], v[144:147], v[196:199], v[12:15]
	v_mfma_f32_16x16x32_bf16 v[4:7], v[152:155], v[196:199], v[4:7]
	s_setprio 0
	s_barrier
	s_add_u32 s36, s46, 0x40080
	s_addc_u32 s37, s47, 0
	s_add_i32 s38, s39, s29
	v_lshl_add_u64 v[138:139], s[36:37], 0, v[168:169]
	s_mov_b32 m0, s38
	s_nop 0
	global_load_lds_dwordx4 v[138:139], off
	v_lshl_add_u64 v[138:139], s[36:37], 0, v[128:129]
	s_add_i32 m0, s38, 0x2000
	s_nop 0
	global_load_lds_dwordx4 v[138:139], off
	s_waitcnt vmcnt(6)
	s_barrier
	s_setprio 1
	v_mfma_f32_16x16x32_bf16 v[56:59], v[200:203], v[156:159], v[56:59]
	v_mfma_f32_16x16x32_bf16 v[48:51], v[208:211], v[156:159], v[48:51]
	v_mfma_f32_16x16x32_bf16 v[40:43], v[200:203], v[164:167], v[40:43]
	v_mfma_f32_16x16x32_bf16 v[32:35], v[208:211], v[164:167], v[32:35]
	v_mfma_f32_16x16x32_bf16 v[24:27], v[200:203], v[184:187], v[24:27]
	v_mfma_f32_16x16x32_bf16 v[16:19], v[208:211], v[184:187], v[16:19]
	v_mfma_f32_16x16x32_bf16 v[8:11], v[200:203], v[192:195], v[8:11]
	v_mfma_f32_16x16x32_bf16 v[0:3], v[208:211], v[192:195], v[0:3]
	v_mfma_f32_16x16x32_bf16 v[56:59], v[204:207], v[160:163], v[56:59]
	v_mfma_f32_16x16x32_bf16 v[48:51], v[212:215], v[160:163], v[48:51]
	v_mfma_f32_16x16x32_bf16 v[40:43], v[204:207], v[180:183], v[40:43]
	v_mfma_f32_16x16x32_bf16 v[32:35], v[212:215], v[180:183], v[32:35]
	v_mfma_f32_16x16x32_bf16 v[24:27], v[204:207], v[188:191], v[24:27]
	v_mfma_f32_16x16x32_bf16 v[16:19], v[212:215], v[188:191], v[16:19]
	v_mfma_f32_16x16x32_bf16 v[8:11], v[204:207], v[196:199], v[8:11]
	v_mfma_f32_16x16x32_bf16 v[0:3], v[212:215], v[196:199], v[0:3]
	s_setprio 0
	s_add_i32 s61, s61, 2
	s_add_u32 s44, s44, 0x100
	s_addc_u32 s45, s45, 0
	s_add_u32 s59, s59, 0x100
	s_addc_u32 s60, s60, 0
	s_cmp_gt_u32 s61, 13
	s_barrier
	s_cbranch_scc0 .LBB0_191
	v_mov_b32_e32 v150, 0xbfb8aa3b
	v_pk_mul_f32 v[148:149], v[124:125], v[150:151] op_sel_hi:[1,0]
	s_nop 0
	v_exp_f32_e32 v148, v148
	v_exp_f32_e32 v149, v149
	s_nop 0
	v_pk_add_f32 v[148:149], v[148:149], 1.0 op_sel_hi:[1,0]
	s_nop 0
	v_rcp_f32_e32 v148, v148
	v_rcp_f32_e32 v149, v149
	v_mov_b32_e32 v138, v171
	s_lshl_b32 s9, s58, 8
	s_add_i32 s9, s9, s52
	v_and_or_b32 v144, v138, 15, s9
	s_lshl_b32 s9, s57, 7
	v_lshrrev_b32_e32 v138, 1, v138
	v_and_or_b32 v138, v138, 24, s9
	v_or_b32_e32 v140, s53, v138
	v_pk_mul_f32 v[124:125], v[124:125], v[148:149]
	v_ashrrev_i32_e32 v141, 31, v140
	v_pk_mul_f32 v[120:121], v[124:125], v[120:121]
	v_mov_b64_e32 v[138:139], s[6:7]
	v_cvt_pk_bf16_f32 v120, v120, v121
	v_pk_mul_f32 v[124:125], v[126:127], v[150:151] op_sel_hi:[1,0]
	s_nop 0
	v_exp_f32_e32 v124, v124
	v_exp_f32_e32 v125, v125
	s_nop 0
	v_pk_add_f32 v[124:125], v[124:125], 1.0 op_sel_hi:[1,0]
	s_nop 0
	v_rcp_f32_e32 v124, v124
	v_rcp_f32_e32 v125, v125
	v_mad_i64_i32 v[146:147], s[34:35], v144, s18, v[138:139]
	v_lshlrev_b64 v[140:141], 1, v[140:141]
	v_lshl_add_u64 v[146:147], v[146:147], 0, v[140:141]
	s_and_b64 vcc, exec, s[40:41]
	s_mov_b32 s57, s8
	s_mov_b32 s58, s12
	s_mov_b64 s[46:47], s[42:43]
	s_mov_b64 s[44:45], s[14:15]
	v_pk_mul_f32 v[124:125], v[126:127], v[124:125]
	s_nop 0
	v_pk_mul_f32 v[122:123], v[124:125], v[122:123]
	s_nop 0
	v_cvt_pk_bf16_f32 v121, v122, v123
	v_pk_mul_f32 v[122:123], v[116:117], v[150:151] op_sel_hi:[1,0]
	s_nop 0
	v_exp_f32_e32 v122, v122
	v_exp_f32_e32 v123, v123
	s_nop 0
	v_pk_add_f32 v[122:123], v[122:123], 1.0 op_sel_hi:[1,0]
	s_nop 0
	v_rcp_f32_e32 v122, v122
	v_rcp_f32_e32 v123, v123
	s_nop 0
	v_pk_mul_f32 v[116:117], v[116:117], v[122:123]
	s_nop 0
	v_pk_mul_f32 v[112:113], v[116:117], v[112:113]
	s_nop 0
	v_cvt_pk_bf16_f32 v122, v112, v113
	v_pk_mul_f32 v[112:113], v[118:119], v[150:151] op_sel_hi:[1,0]
	s_nop 0
	v_exp_f32_e32 v112, v112
	v_exp_f32_e32 v113, v113
	s_nop 0
	v_pk_add_f32 v[112:113], v[112:113], 1.0 op_sel_hi:[1,0]
	s_nop 0
	v_rcp_f32_e32 v112, v112
	v_rcp_f32_e32 v113, v113
	s_nop 0
	v_pk_mul_f32 v[112:113], v[118:119], v[112:113]
	s_nop 0
	v_pk_mul_f32 v[112:113], v[112:113], v[114:115]
	v_pk_mul_f32 v[114:115], v[108:109], v[150:151] op_sel_hi:[1,0]
	s_nop 0
	v_exp_f32_e32 v114, v114
	v_exp_f32_e32 v115, v115
	s_nop 0
	v_pk_add_f32 v[114:115], v[114:115], 1.0 op_sel_hi:[1,0]
	s_nop 0
	v_rcp_f32_e32 v114, v114
	v_rcp_f32_e32 v115, v115
	v_cvt_pk_bf16_f32 v123, v112, v113
	v_or_b32_e32 v112, 16, v144
	v_mad_i64_i32 v[112:113], s[34:35], v112, s18, v[138:139]
	global_store_dwordx4 v[146:147], v[120:123], off
	v_pk_mul_f32 v[108:109], v[108:109], v[114:115]
	v_lshl_add_u64 v[112:113], v[112:113], 0, v[140:141]
	v_pk_mul_f32 v[104:105], v[108:109], v[104:105]
	s_nop 0
	v_cvt_pk_bf16_f32 v104, v104, v105
	v_pk_mul_f32 v[108:109], v[110:111], v[150:151] op_sel_hi:[1,0]
	s_nop 0
	v_exp_f32_e32 v108, v108
	v_exp_f32_e32 v109, v109
	s_nop 0
	v_pk_add_f32 v[108:109], v[108:109], 1.0 op_sel_hi:[1,0]
	s_nop 0
	v_rcp_f32_e32 v108, v108
	v_rcp_f32_e32 v109, v109
	s_nop 0
	v_pk_mul_f32 v[108:109], v[110:111], v[108:109]
	s_nop 0
	v_pk_mul_f32 v[106:107], v[108:109], v[106:107]
	s_nop 0
	v_cvt_pk_bf16_f32 v105, v106, v107
	v_pk_mul_f32 v[106:107], v[100:101], v[150:151] op_sel_hi:[1,0]
	s_nop 0
	v_exp_f32_e32 v106, v106
	v_exp_f32_e32 v107, v107
	s_nop 0
	v_pk_add_f32 v[106:107], v[106:107], 1.0 op_sel_hi:[1,0]
	s_nop 0
	v_rcp_f32_e32 v106, v106
	v_rcp_f32_e32 v107, v107
	s_nop 0
	v_pk_mul_f32 v[100:101], v[100:101], v[106:107]
	s_nop 0
	v_pk_mul_f32 v[96:97], v[100:101], v[96:97]
	s_nop 0
	v_cvt_pk_bf16_f32 v106, v96, v97
	v_pk_mul_f32 v[96:97], v[102:103], v[150:151] op_sel_hi:[1,0]
	s_nop 0
	v_exp_f32_e32 v96, v96
	v_exp_f32_e32 v97, v97
	s_nop 0
	v_pk_add_f32 v[96:97], v[96:97], 1.0 op_sel_hi:[1,0]
	s_nop 0
	v_rcp_f32_e32 v96, v96
	v_rcp_f32_e32 v97, v97
	s_nop 0
	v_pk_mul_f32 v[96:97], v[102:103], v[96:97]
	s_nop 0
	v_pk_mul_f32 v[96:97], v[96:97], v[98:99]
	v_pk_mul_f32 v[98:99], v[92:93], v[150:151] op_sel_hi:[1,0]
	s_nop 0
	v_exp_f32_e32 v98, v98
	v_exp_f32_e32 v99, v99
	s_nop 0
	v_pk_add_f32 v[98:99], v[98:99], 1.0 op_sel_hi:[1,0]
	s_nop 0
	v_rcp_f32_e32 v98, v98
	v_rcp_f32_e32 v99, v99
	v_cvt_pk_bf16_f32 v107, v96, v97
	v_or_b32_e32 v96, 32, v144
	v_mad_i64_i32 v[96:97], s[34:35], v96, s18, v[138:139]
	global_store_dwordx4 v[112:113], v[104:107], off
	v_pk_mul_f32 v[92:93], v[92:93], v[98:99]
	v_lshl_add_u64 v[96:97], v[96:97], 0, v[140:141]
	v_pk_mul_f32 v[88:89], v[92:93], v[88:89]
	s_nop 0
	v_cvt_pk_bf16_f32 v88, v88, v89
	v_pk_mul_f32 v[92:93], v[94:95], v[150:151] op_sel_hi:[1,0]
	s_nop 0
	v_exp_f32_e32 v92, v92
	v_exp_f32_e32 v93, v93
	s_nop 0
	v_pk_add_f32 v[92:93], v[92:93], 1.0 op_sel_hi:[1,0]
	s_nop 0
	v_rcp_f32_e32 v92, v92
	v_rcp_f32_e32 v93, v93
	s_nop 0
	v_pk_mul_f32 v[92:93], v[94:95], v[92:93]
	s_nop 0
	v_pk_mul_f32 v[90:91], v[92:93], v[90:91]
	s_nop 0
	v_cvt_pk_bf16_f32 v89, v90, v91
	v_pk_mul_f32 v[90:91], v[84:85], v[150:151] op_sel_hi:[1,0]
	s_nop 0
	v_exp_f32_e32 v90, v90
	v_exp_f32_e32 v91, v91
	s_nop 0
	v_pk_add_f32 v[90:91], v[90:91], 1.0 op_sel_hi:[1,0]
	s_nop 0
	v_rcp_f32_e32 v90, v90
	v_rcp_f32_e32 v91, v91
	s_nop 0
	v_pk_mul_f32 v[84:85], v[84:85], v[90:91]
	s_nop 0
	v_pk_mul_f32 v[80:81], v[84:85], v[80:81]
	s_nop 0
	v_cvt_pk_bf16_f32 v90, v80, v81
	v_pk_mul_f32 v[80:81], v[86:87], v[150:151] op_sel_hi:[1,0]
	s_nop 0
	v_exp_f32_e32 v80, v80
	v_exp_f32_e32 v81, v81
	s_nop 0
	v_pk_add_f32 v[80:81], v[80:81], 1.0 op_sel_hi:[1,0]
	s_nop 0
	v_rcp_f32_e32 v80, v80
	v_rcp_f32_e32 v81, v81
	s_nop 0
	v_pk_mul_f32 v[80:81], v[86:87], v[80:81]
	s_nop 0
	v_pk_mul_f32 v[80:81], v[80:81], v[82:83]
	v_pk_mul_f32 v[82:83], v[76:77], v[150:151] op_sel_hi:[1,0]
	s_nop 0
	v_exp_f32_e32 v82, v82
	v_exp_f32_e32 v83, v83
	s_nop 0
	v_pk_add_f32 v[82:83], v[82:83], 1.0 op_sel_hi:[1,0]
	s_nop 0
	v_rcp_f32_e32 v82, v82
	v_rcp_f32_e32 v83, v83
	v_cvt_pk_bf16_f32 v91, v80, v81
	v_or_b32_e32 v80, 48, v144
	v_mad_i64_i32 v[80:81], s[34:35], v80, s18, v[138:139]
	global_store_dwordx4 v[96:97], v[88:91], off
	v_pk_mul_f32 v[76:77], v[76:77], v[82:83]
	v_lshl_add_u64 v[80:81], v[80:81], 0, v[140:141]
	v_pk_mul_f32 v[72:73], v[76:77], v[72:73]
	s_nop 0
	v_cvt_pk_bf16_f32 v72, v72, v73
	v_pk_mul_f32 v[76:77], v[78:79], v[150:151] op_sel_hi:[1,0]
	s_nop 0
	v_exp_f32_e32 v76, v76
	v_exp_f32_e32 v77, v77
	s_nop 0
	v_pk_add_f32 v[76:77], v[76:77], 1.0 op_sel_hi:[1,0]
	s_nop 0
	v_rcp_f32_e32 v76, v76
	v_rcp_f32_e32 v77, v77
	s_nop 0
	v_pk_mul_f32 v[76:77], v[78:79], v[76:77]
	s_nop 0
	v_pk_mul_f32 v[74:75], v[76:77], v[74:75]
	s_nop 0
	v_cvt_pk_bf16_f32 v73, v74, v75
	v_pk_mul_f32 v[74:75], v[68:69], v[150:151] op_sel_hi:[1,0]
	s_nop 0
	v_exp_f32_e32 v74, v74
	v_exp_f32_e32 v75, v75
	s_nop 0
	v_pk_add_f32 v[74:75], v[74:75], 1.0 op_sel_hi:[1,0]
	s_nop 0
	v_rcp_f32_e32 v74, v74
	v_rcp_f32_e32 v75, v75
	s_nop 0
	v_pk_mul_f32 v[68:69], v[68:69], v[74:75]
	s_nop 0
	v_pk_mul_f32 v[64:65], v[68:69], v[64:65]
	s_nop 0
	v_cvt_pk_bf16_f32 v74, v64, v65
	v_pk_mul_f32 v[64:65], v[70:71], v[150:151] op_sel_hi:[1,0]
	s_nop 0
	v_exp_f32_e32 v64, v64
	v_exp_f32_e32 v65, v65
	s_nop 0
	v_pk_add_f32 v[64:65], v[64:65], 1.0 op_sel_hi:[1,0]
	s_nop 0
	v_rcp_f32_e32 v64, v64
	v_rcp_f32_e32 v65, v65
	s_nop 0
	v_pk_mul_f32 v[64:65], v[70:71], v[64:65]
	s_nop 0
	v_pk_mul_f32 v[64:65], v[64:65], v[66:67]
	v_pk_mul_f32 v[66:67], v[60:61], v[150:151] op_sel_hi:[1,0]
	s_nop 0
	v_exp_f32_e32 v66, v66
	v_exp_f32_e32 v67, v67
	s_nop 0
	v_pk_add_f32 v[66:67], v[66:67], 1.0 op_sel_hi:[1,0]
	s_nop 0
	v_rcp_f32_e32 v66, v66
	v_rcp_f32_e32 v67, v67
	v_cvt_pk_bf16_f32 v75, v64, v65
	v_add_u32_e32 v64, 0x80, v144
	v_mad_i64_i32 v[64:65], s[34:35], v64, s18, v[138:139]
	global_store_dwordx4 v[80:81], v[72:75], off
	v_pk_mul_f32 v[60:61], v[60:61], v[66:67]
	v_lshl_add_u64 v[64:65], v[64:65], 0, v[140:141]
	v_pk_mul_f32 v[56:57], v[60:61], v[56:57]
	s_nop 0
	v_cvt_pk_bf16_f32 v56, v56, v57
	v_pk_mul_f32 v[60:61], v[62:63], v[150:151] op_sel_hi:[1,0]
	s_nop 0
	v_exp_f32_e32 v60, v60
	v_exp_f32_e32 v61, v61
	s_nop 0
	v_pk_add_f32 v[60:61], v[60:61], 1.0 op_sel_hi:[1,0]
	s_nop 0
	v_rcp_f32_e32 v60, v60
	v_rcp_f32_e32 v61, v61
	s_nop 0
	v_pk_mul_f32 v[60:61], v[62:63], v[60:61]
	s_nop 0
	v_pk_mul_f32 v[58:59], v[60:61], v[58:59]
	s_nop 0
	v_cvt_pk_bf16_f32 v57, v58, v59
	v_pk_mul_f32 v[58:59], v[52:53], v[150:151] op_sel_hi:[1,0]
	s_nop 0
	v_exp_f32_e32 v58, v58
	v_exp_f32_e32 v59, v59
	s_nop 0
	v_pk_add_f32 v[58:59], v[58:59], 1.0 op_sel_hi:[1,0]
	s_nop 0
	v_rcp_f32_e32 v58, v58
	v_rcp_f32_e32 v59, v59
	s_nop 0
	v_pk_mul_f32 v[52:53], v[52:53], v[58:59]
	s_nop 0
	v_pk_mul_f32 v[48:49], v[52:53], v[48:49]
	s_nop 0
	v_cvt_pk_bf16_f32 v58, v48, v49
	v_pk_mul_f32 v[48:49], v[54:55], v[150:151] op_sel_hi:[1,0]
	s_nop 0
	v_exp_f32_e32 v48, v48
	v_exp_f32_e32 v49, v49
	s_nop 0
	v_pk_add_f32 v[48:49], v[48:49], 1.0 op_sel_hi:[1,0]
	s_nop 0
	v_rcp_f32_e32 v48, v48
	v_rcp_f32_e32 v49, v49
	s_nop 0
	v_pk_mul_f32 v[48:49], v[54:55], v[48:49]
	s_nop 0
	v_pk_mul_f32 v[48:49], v[48:49], v[50:51]
	v_pk_mul_f32 v[50:51], v[44:45], v[150:151] op_sel_hi:[1,0]
	s_nop 0
	v_exp_f32_e32 v50, v50
	v_exp_f32_e32 v51, v51
	s_nop 0
	v_pk_add_f32 v[50:51], v[50:51], 1.0 op_sel_hi:[1,0]
	s_nop 0
	v_rcp_f32_e32 v50, v50
	v_rcp_f32_e32 v51, v51
	v_cvt_pk_bf16_f32 v59, v48, v49
	v_add_u32_e32 v48, 0x90, v144
	v_mad_i64_i32 v[48:49], s[34:35], v48, s18, v[138:139]
	global_store_dwordx4 v[64:65], v[56:59], off
	v_pk_mul_f32 v[44:45], v[44:45], v[50:51]
	v_lshl_add_u64 v[48:49], v[48:49], 0, v[140:141]
	v_pk_mul_f32 v[40:41], v[44:45], v[40:41]
	s_nop 0
	v_cvt_pk_bf16_f32 v40, v40, v41
	v_pk_mul_f32 v[44:45], v[46:47], v[150:151] op_sel_hi:[1,0]
	s_nop 0
	v_exp_f32_e32 v44, v44
	v_exp_f32_e32 v45, v45
	s_nop 0
	v_pk_add_f32 v[44:45], v[44:45], 1.0 op_sel_hi:[1,0]
	s_nop 0
	v_rcp_f32_e32 v44, v44
	v_rcp_f32_e32 v45, v45
	s_nop 0
	v_pk_mul_f32 v[44:45], v[46:47], v[44:45]
	s_nop 0
	v_pk_mul_f32 v[42:43], v[44:45], v[42:43]
	s_nop 0
	v_cvt_pk_bf16_f32 v41, v42, v43
	v_pk_mul_f32 v[42:43], v[36:37], v[150:151] op_sel_hi:[1,0]
	s_nop 0
	v_exp_f32_e32 v42, v42
	v_exp_f32_e32 v43, v43
	s_nop 0
	v_pk_add_f32 v[42:43], v[42:43], 1.0 op_sel_hi:[1,0]
	s_nop 0
	v_rcp_f32_e32 v42, v42
	v_rcp_f32_e32 v43, v43
	s_nop 0
	v_pk_mul_f32 v[36:37], v[36:37], v[42:43]
	s_nop 0
	v_pk_mul_f32 v[32:33], v[36:37], v[32:33]
	s_nop 0
	v_cvt_pk_bf16_f32 v42, v32, v33
	v_pk_mul_f32 v[32:33], v[38:39], v[150:151] op_sel_hi:[1,0]
	s_nop 0
	v_exp_f32_e32 v32, v32
	v_exp_f32_e32 v33, v33
	s_nop 0
	v_pk_add_f32 v[32:33], v[32:33], 1.0 op_sel_hi:[1,0]
	s_nop 0
	v_rcp_f32_e32 v32, v32
	v_rcp_f32_e32 v33, v33
	s_nop 0
	v_pk_mul_f32 v[32:33], v[38:39], v[32:33]
	s_nop 0
	v_pk_mul_f32 v[32:33], v[32:33], v[34:35]
	v_pk_mul_f32 v[34:35], v[28:29], v[150:151] op_sel_hi:[1,0]
	s_nop 0
	v_exp_f32_e32 v34, v34
	v_exp_f32_e32 v35, v35
	s_nop 0
	v_pk_add_f32 v[34:35], v[34:35], 1.0 op_sel_hi:[1,0]
	s_nop 0
	v_rcp_f32_e32 v34, v34
	v_rcp_f32_e32 v35, v35
	v_cvt_pk_bf16_f32 v43, v32, v33
	v_add_u32_e32 v32, 0xa0, v144
	v_mad_i64_i32 v[32:33], s[34:35], v32, s18, v[138:139]
	global_store_dwordx4 v[48:49], v[40:43], off
	v_pk_mul_f32 v[28:29], v[28:29], v[34:35]
	v_lshl_add_u64 v[32:33], v[32:33], 0, v[140:141]
	v_pk_mul_f32 v[24:25], v[28:29], v[24:25]
	s_nop 0
	v_cvt_pk_bf16_f32 v24, v24, v25
	v_pk_mul_f32 v[28:29], v[30:31], v[150:151] op_sel_hi:[1,0]
	s_nop 0
	v_exp_f32_e32 v28, v28
	v_exp_f32_e32 v29, v29
	s_nop 0
	v_pk_add_f32 v[28:29], v[28:29], 1.0 op_sel_hi:[1,0]
	s_nop 0
	v_rcp_f32_e32 v28, v28
	v_rcp_f32_e32 v29, v29
	s_nop 0
	v_pk_mul_f32 v[28:29], v[30:31], v[28:29]
	s_nop 0
	v_pk_mul_f32 v[26:27], v[28:29], v[26:27]
	s_nop 0
	v_cvt_pk_bf16_f32 v25, v26, v27
	v_pk_mul_f32 v[26:27], v[20:21], v[150:151] op_sel_hi:[1,0]
	s_nop 0
	v_exp_f32_e32 v26, v26
	v_exp_f32_e32 v27, v27
	s_nop 0
	v_pk_add_f32 v[26:27], v[26:27], 1.0 op_sel_hi:[1,0]
	s_nop 0
	v_rcp_f32_e32 v26, v26
	v_rcp_f32_e32 v27, v27
	s_nop 0
	v_pk_mul_f32 v[20:21], v[20:21], v[26:27]
	s_nop 0
	v_pk_mul_f32 v[16:17], v[20:21], v[16:17]
	s_nop 0
	v_cvt_pk_bf16_f32 v26, v16, v17
	v_pk_mul_f32 v[16:17], v[22:23], v[150:151] op_sel_hi:[1,0]
	s_nop 0
	v_exp_f32_e32 v16, v16
	v_exp_f32_e32 v17, v17
	s_nop 0
	v_pk_add_f32 v[16:17], v[16:17], 1.0 op_sel_hi:[1,0]
	s_nop 0
	v_rcp_f32_e32 v16, v16
	v_rcp_f32_e32 v17, v17
	s_nop 0
	v_pk_mul_f32 v[16:17], v[22:23], v[16:17]
	s_nop 0
	v_pk_mul_f32 v[16:17], v[16:17], v[18:19]
	v_pk_mul_f32 v[18:19], v[12:13], v[150:151] op_sel_hi:[1,0]
	s_nop 0
	v_exp_f32_e32 v18, v18
	v_exp_f32_e32 v19, v19
	s_nop 0
	v_pk_add_f32 v[18:19], v[18:19], 1.0 op_sel_hi:[1,0]
	s_nop 0
	v_rcp_f32_e32 v18, v18
	v_rcp_f32_e32 v19, v19
	v_cvt_pk_bf16_f32 v27, v16, v17
	v_add_u32_e32 v16, 0xb0, v144
	v_mad_i64_i32 v[16:17], s[34:35], v16, s18, v[138:139]
	global_store_dwordx4 v[32:33], v[24:27], off
	v_pk_mul_f32 v[12:13], v[12:13], v[18:19]
	v_lshl_add_u64 v[16:17], v[16:17], 0, v[140:141]
	v_pk_mul_f32 v[8:9], v[12:13], v[8:9]
	s_nop 0
	v_cvt_pk_bf16_f32 v8, v8, v9
	v_pk_mul_f32 v[12:13], v[14:15], v[150:151] op_sel_hi:[1,0]
	s_nop 0
	v_exp_f32_e32 v12, v12
	v_exp_f32_e32 v13, v13
	s_nop 0
	v_pk_add_f32 v[12:13], v[12:13], 1.0 op_sel_hi:[1,0]
	s_nop 0
	v_rcp_f32_e32 v12, v12
	v_rcp_f32_e32 v13, v13
	s_nop 0
	v_pk_mul_f32 v[12:13], v[14:15], v[12:13]
	s_nop 0
	v_pk_mul_f32 v[10:11], v[12:13], v[10:11]
	s_nop 0
	v_cvt_pk_bf16_f32 v9, v10, v11
	v_pk_mul_f32 v[10:11], v[4:5], v[150:151] op_sel_hi:[1,0]
	s_nop 0
	v_exp_f32_e32 v10, v10
	v_exp_f32_e32 v11, v11
	s_nop 0
	v_pk_add_f32 v[10:11], v[10:11], 1.0 op_sel_hi:[1,0]
	s_nop 0
	v_rcp_f32_e32 v10, v10
	v_rcp_f32_e32 v11, v11
	s_nop 0
	v_pk_mul_f32 v[4:5], v[4:5], v[10:11]
	s_nop 0
	v_pk_mul_f32 v[0:1], v[4:5], v[0:1]
	s_nop 0
	v_cvt_pk_bf16_f32 v10, v0, v1
	v_pk_mul_f32 v[0:1], v[6:7], v[150:151] op_sel_hi:[1,0]
	s_nop 0
	v_exp_f32_e32 v0, v0
	v_exp_f32_e32 v1, v1
	s_nop 0
	v_pk_add_f32 v[0:1], v[0:1], 1.0 op_sel_hi:[1,0]
	s_nop 0
	v_rcp_f32_e32 v0, v0
	v_rcp_f32_e32 v1, v1
	s_nop 0
	v_pk_mul_f32 v[0:1], v[6:7], v[0:1]
	s_nop 0
	v_pk_mul_f32 v[0:1], v[0:1], v[2:3]
	s_nop 0
	v_cvt_pk_bf16_f32 v11, v0, v1
	global_store_dwordx4 v[16:17], v[8:11], off
	s_cbranch_vccz .LBB0_188
	s_waitcnt vmcnt(0)
	s_cmpk_gt_u32 s16, 0xff
	s_cbranch_scc1 .LBB0_195
	s_barrier
